# v53 + static s_setprio 1 for the trailing wave half during GEMM phases (no per-segment toggles)
# speedup vs baseline: 1.0085x; 1.0085x over previous
; #define PG8_STAGE(bufoff, gbase, voff) do { _Pragma("unroll") for (int _i = 0; _i < 2; ++_i) \
;         __builtin_amdgcn_global_load_lds((const unsigned*)((const char*)(gbase) + (voff)[_i]), (PG8_LAS unsigned*)(lds + (bufoff) + ldsw + _i * 8192), 16, 0, 0); } while (0)
; #define PG8_BAR __builtin_amdgcn_s_barrier()
;     __device__ __forceinline__ PrepRegs prep_issue(const Unit& u, int tid) const { return rs_issue(SSQ, u, tid); }
;     __device__ __forceinline__ PrepRegs prep_issue(const Unit& u, int tid) const { return rs_issue(SSQ, u, tid); }
; template <class Epi, class Sched, bool ALIGN_EPI = false, bool SP2 = false>
; __device__ __forceinline__ void gemm_phase(PG8_LAS unsigned char* lds, const Gemm g, const Sched& S, const Epi& E) {
;     ...
;     const int tid = tid_o, wid = __builtin_amdgcn_readfirstlane(tid >> 6), lane = tid & 63, wr = wid >> 2, wc = wid & 3, fr = lane & 15, fq = lane >> 4;
;     const int K = g.K, nt = K / BK;
;     unsigned voffA[2], voffB[2];
; #pragma unroll
;     for (int i = 0; i < 2; ++i) { int R, C; stage_rc(tid * 16 + i * 8192, R, C); const int Rb = Epi::PERM ? ((R & ~31) + perm32(R & 31)) : R;
;         voffA[i] = (unsigned)(R * K + C) * 2u; voffB[i] = (unsigned)(Rb * K + C) * 2u; }
;     const size_t kstep = (size_t)(BK * 2);
;     const size_t hstep = (size_t)HALF * K * 2;
;     const size_t tstep = 2 * hstep;
;     const unsigned ldsw = (unsigned)wid * 1024u;
;     const int aoff = lds_byte(wr * 64 + fr, fq * 8), boff = lds_byte(wc * 32 + fr, fq * 8);
;     ...
;     Unit cur, nxt; int ui = 0;
;     if (!S.next(0, cur)) return;
;     f32x4 acc[2][2][4][2];
; #pragma unroll
;     for (int a = 0; a < 2; ++a)
; #pragma unroll
;         for (int b = 0; b < 2; ++b)
; #pragma unroll
;             for (int m = 0; m < 4; ++m)
; #pragma unroll
;                 for (int n = 0; n < 2; ++n) acc[a][b][m][n] = (f32x4){0.f, 0.f, 0.f, 0.f};
;     bf16x8 At[4][2], B0[2][2], B1[2][2];
;     const char* cA = (const char*)g.A + (size_t)cur.pm * tstep; const char* cB = (const char*)g.Bt + (size_t)cur.pn * tstep;
;     S.a_ready(cur);
;     { const auto pr0 = E.prep_issue(cur, tid); E.prep_commit(lds, pr0, 0, tid); }
;     if constexpr (SP2) {
;         PG8_STAGE(PG8_SB(0, 0), cB, voffB); PG8_STAGE(PG8_SB(0, 1), cB + hstep, voffB); PG8_STAGE(PG8_SA(0, 0), cA, voffA); PG8_STAGE(PG8_SA(0, 1), cA + hstep, voffA);
;         if (wr == 1) PG8_BAR;
.LBB0_180:
	s_or_b64 exec, exec, s[8:9]
	s_waitcnt lgkmcnt(0)
	v_ashrrev_i32_e32 v3, 31, v6
	v_lshrrev_b32_e32 v3, 26, v3
	v_add_u32_e32 v3, v6, v3
	v_ashrrev_i32_e32 v7, 6, v3
	v_bfe_i32 v3, v6, 27, 1
	v_lshlrev_b32_e32 v2, 4, v6
	v_lshrrev_b32_e32 v3, 22, v3
	v_add_u32_e32 v3, v2, v3
	v_and_b32_e32 v3, 0xfffffc00, v3
	v_sub_u32_e32 v3, v2, v3
	v_lshrrev_b32_e32 v4, 4, v3
	v_bitop3_b32 v3, v4, v3, 32 bitop3:0x6c
	v_ashrrev_i32_e32 v5, 31, v3
	v_lshrrev_b32_e32 v5, 26, v5
	v_add_u32_e32 v5, v3, v5
	v_lshlrev_b32_e32 v4, 3, v7
	v_ashrrev_i32_e32 v8, 6, v5
	v_and_b32_e32 v5, 0xc0, v5
	v_and_b32_e32 v4, -16, v4
	v_sub_u32_e32 v3, v3, v5
	v_add_u32_e32 v4, v8, v4
	v_lshlrev_b32_e32 v9, 5, v7
	v_ashrrev_i16_sdwa v3, v213, sext(v3) dst_sel:DWORD dst_unused:UNUSED_PAD src0_sel:DWORD src1_sel:BYTE_0
	v_and_b32_e32 v10, 32, v9
	v_bfe_i32 v9, v3, 0, 16
	v_lshlrev_b32_e32 v3, 1, v4
	v_lshrrev_b32_e32 v5, 2, v4
	v_and_b32_e32 v11, 3, v8
	s_mov_b32 s6, 0x1fffe0
	v_and_b32_e32 v3, 24, v3
	v_and_b32_e32 v5, 4, v5
	v_and_or_b32 v11, v4, s6, v11
	v_or3_b32 v3, v11, v5, v3
	v_add_lshl_u32 v5, v10, v9, 1
	v_add_u32_e32 v2, 0x2000, v2
	v_lshl_add_u32 v156, v3, 11, v5
	v_ashrrev_i32_e32 v3, 31, v2
	v_lshrrev_b32_e32 v3, 22, v3
	v_add_u32_e32 v3, v2, v3
	v_ashrrev_i32_e32 v10, 10, v3
	v_mul_i32_i24_e32 v3, 0x400, v10
	v_sub_u32_e32 v2, v2, v3
	v_lshrrev_b32_e32 v3, 4, v2
	v_bitop3_b32 v2, v3, v2, 32 bitop3:0x6c
	v_lshl_add_u32 v154, v4, 11, v5
	v_ashrrev_i32_e32 v4, 31, v2
	v_lshrrev_b32_e32 v4, 26, v4
	v_readlane_b32 s8, v254, 37
	v_readlane_b32 s3, v255, 4
	v_add_u32_e32 v4, v2, v4
	v_readlane_b32 s9, v254, 38
	s_add_u32 s10, s3, s8
	v_readlane_b32 s3, v255, 5
	v_lshlrev_b32_e32 v3, 3, v10
	v_ashrrev_i32_e32 v11, 6, v4
	v_and_b32_e32 v4, 0xc0, v4
	s_addc_u32 s11, s3, s9
	s_ashr_i32 s3, s2, 6
	v_and_b32_e32 v3, -16, v3
	v_sub_u32_e32 v2, v2, v4
	v_add_u32_e32 v3, v11, v3
	v_ashrrev_i16_sdwa v2, v213, sext(v2) dst_sel:DWORD dst_unused:UNUSED_PAD src0_sel:DWORD src1_sel:BYTE_0
	s_lshl_b32 s20, s3, 10
	v_lshlrev_b32_e32 v5, 5, v10
	v_bfe_i32 v12, v2, 0, 16
	v_lshlrev_b32_e32 v2, 1, v3
	v_lshrrev_b32_e32 v4, 2, v3
	v_and_b32_e32 v13, 3, v11
	s_add_i32 s21, s20, 0
	v_and_b32_e32 v5, 32, v5
	v_and_b32_e32 v2, 24, v2
	v_and_b32_e32 v4, 4, v4
	v_and_or_b32 v13, v3, s6, v13
	s_add_i32 m0, s21, 0x10000
	v_or3_b32 v2, v13, v4, v2
	v_add_lshl_u32 v4, v5, v12, 1
	s_ashr_i32 s6, s2, 8
	global_load_lds_dwordx4 v156, s[10:11]
	s_add_i32 m0, s21, 0x12000
	v_lshl_add_u32 v160, v2, 11, v4
	s_add_u32 s8, s10, 0x40000
	global_load_lds_dwordx4 v160, s[10:11]
	s_addc_u32 s9, s11, 0
	s_add_i32 m0, s21, 0x14000
	s_add_i32 s45, s21, 0x2000
	global_load_lds_dwordx4 v156, s[8:9]
	s_add_i32 m0, s21, 0x16000
	v_lshl_add_u32 v158, v3, 11, v4
	global_load_lds_dwordx4 v160, s[8:9]
	v_readlane_b32 s8, v254, 42
	s_mov_b32 m0, s21
	v_readlane_b32 s9, v254, 43
	s_add_i32 s62, s21, 0x4000
	s_add_i32 s63, s21, 0x6000
	v_mov_b32_e32 v157, v1
	v_mov_b32_e32 v161, v1
	s_cmp_eq_u32 s6, 1
	global_load_lds_dwordx4 v154, s[8:9]
	s_mov_b32 m0, s45
	v_lshl_add_u64 v[2:3], s[10:11], 0, v[156:157]
	global_load_lds_dwordx4 v158, s[8:9]
	v_readlane_b32 s8, v254, 44
	s_mov_b32 m0, s62
	v_readlane_b32 s9, v254, 45
	s_cselect_b64 s[46:47], -1, 0
	s_cmp_lg_u32 s6, 1
	v_lshl_add_u64 v[4:5], s[10:11], 0, v[160:161]
	s_nop 1
	global_load_lds_dwordx4 v154, s[8:9]
	s_mov_b32 m0, s63
	s_nop 0
	global_load_lds_dwordx4 v158, s[8:9]
	s_cbranch_scc1 .LBB0_182
	s_setprio 1
	s_barrier

; #define PG8_WAIT_V(n) asm volatile("s_waitcnt vmcnt(" #n ")" ::: "memory")
; #define PG8_BAR __builtin_amdgcn_s_barrier()
; template <class Epi, class Sched, bool ALIGN_EPI = false, bool SP2 = false>
; __device__ __forceinline__ void gemm_phase(PG8_LAS unsigned char* lds, const Gemm g, const Sched& S, const Epi& E) {
;     ...
;     PG8_WAIT_V(0);
;     if constexpr (!ALIGN_EPI) { if (wr == 0) PG8_BAR; }
;     PG8_BAR;
.LBB0_316:
	s_setprio 0
	s_waitcnt vmcnt(0)
	s_barrier

; #define PG8_STAGE(bufoff, gbase, voff) do { _Pragma("unroll") for (int _i = 0; _i < 2; ++_i) \
;         __builtin_amdgcn_global_load_lds((const unsigned*)((const char*)(gbase) + (voff)[_i]), (PG8_LAS unsigned*)(lds + (bufoff) + ldsw + _i * 8192), 16, 0, 0); } while (0)
; #define PG8_BAR __builtin_amdgcn_s_barrier()
;     __device__ __forceinline__ PrepRegs prep_issue(const Unit& u, int tid) const { return rs_issue(SSQ, u, tid); }
;     __device__ __forceinline__ PrepRegs prep_issue(const Unit& u, int tid) const { return rs_issue(SSQ, u, tid); }
; template <class Epi, class Sched, bool ALIGN_EPI = false, bool SP2 = false>
; __device__ __forceinline__ void gemm_phase(PG8_LAS unsigned char* lds, const Gemm g, const Sched& S, const Epi& E) {
;     ...
;     const int tid = tid_o, wid = __builtin_amdgcn_readfirstlane(tid >> 6), lane = tid & 63, wr = wid >> 2, wc = wid & 3, fr = lane & 15, fq = lane >> 4;
;     const int K = g.K, nt = K / BK;
;     unsigned voffA[2], voffB[2];
; #pragma unroll
;     for (int i = 0; i < 2; ++i) { int R, C; stage_rc(tid * 16 + i * 8192, R, C); const int Rb = Epi::PERM ? ((R & ~31) + perm32(R & 31)) : R;
;         voffA[i] = (unsigned)(R * K + C) * 2u; voffB[i] = (unsigned)(Rb * K + C) * 2u; }
;     const size_t kstep = (size_t)(BK * 2);
;     const size_t hstep = (size_t)HALF * K * 2;
;     const size_t tstep = 2 * hstep;
;     const unsigned ldsw = (unsigned)wid * 1024u;
;     const int aoff = lds_byte(wr * 64 + fr, fq * 8), boff = lds_byte(wc * 32 + fr, fq * 8);
;     ...
;     Unit cur, nxt; int ui = 0;
;     if (!S.next(0, cur)) return;
;     f32x4 acc[2][2][4][2];
; #pragma unroll
;     for (int a = 0; a < 2; ++a)
; #pragma unroll
;         for (int b = 0; b < 2; ++b)
; #pragma unroll
;             for (int m = 0; m < 4; ++m)
; #pragma unroll
;                 for (int n = 0; n < 2; ++n) acc[a][b][m][n] = (f32x4){0.f, 0.f, 0.f, 0.f};
;     bf16x8 At[4][2], B0[2][2], B1[2][2];
;     const char* cA = (const char*)g.A + (size_t)cur.pm * tstep; const char* cB = (const char*)g.Bt + (size_t)cur.pn * tstep;
;     S.a_ready(cur);
;     { const auto pr0 = E.prep_issue(cur, tid); E.prep_commit(lds, pr0, 0, tid); }
;     if constexpr (SP2) {
;         PG8_STAGE(PG8_SB(0, 0), cB, voffB); PG8_STAGE(PG8_SB(0, 1), cB + hstep, voffB); PG8_STAGE(PG8_SA(0, 0), cA, voffA); PG8_STAGE(PG8_SA(0, 1), cA + hstep, voffA);
;         if (wr == 1) PG8_BAR;
.LBB0_663:
	s_or_b64 exec, exec, s[4:5]
	v_readlane_b32 s4, v254, 17
	v_readlane_b32 s2, v255, 4
	v_readlane_b32 s5, v254, 18
	s_add_u32 s2, s2, 0x500000
	v_readlane_b32 s3, v255, 5
	v_mov_b32_e32 v8, v212
	v_cndmask_b32_e64 v0, 0, 1, s[4:5]
	s_waitcnt lgkmcnt(0)
	s_barrier
	s_addc_u32 s3, s3, 0
	v_cmp_ne_u32_e64 s[38:39], 1, v0
	s_andn2_b64 vcc, exec, s[4:5]
	v_readfirstlane_b32 s6, v8
	s_cbranch_vccnz .LBB0_703
	v_lshlrev_b32_e32 v0, 4, v8
	v_add_u32_e32 v3, 0x2000, v0
	v_ashrrev_i32_e32 v2, 31, v3
	v_lshrrev_b32_e32 v2, 22, v2
	v_add_u32_e32 v2, v3, v2
	v_ashrrev_i32_e32 v2, 10, v2
	v_mul_i32_i24_e32 v4, 0x400, v2
	v_sub_u32_e32 v3, v3, v4
	v_lshrrev_b32_e32 v4, 4, v3
	v_bitop3_b32 v4, v4, v3, 32 bitop3:0x6c
	v_ashrrev_i32_e32 v3, 31, v4
	v_lshrrev_b32_e32 v3, 26, v3
	v_add_u32_e32 v5, v4, v3
	v_lshlrev_b32_e32 v6, 3, v2
	v_ashrrev_i32_e32 v3, 6, v5
	v_and_b32_e32 v6, -16, v6
	v_add_u32_e32 v6, v3, v6
	v_and_b32_e32 v7, 3, v3
	s_mov_b32 s4, 0x1fffe0
	v_lshrrev_b32_e32 v9, 2, v6
	v_lshlrev_b32_e32 v10, 1, v6
	v_and_b32_e32 v5, 0xc0, v5
	v_and_or_b32 v7, v6, s4, v7
	v_and_b32_e32 v9, 4, v9
	v_and_b32_e32 v10, 24, v10
	v_sub_u32_e32 v4, v4, v5
	v_or3_b32 v7, v7, v9, v10
	v_lshlrev_b32_e32 v9, 5, v2
	v_ashrrev_i16_sdwa v4, v213, sext(v4) dst_sel:DWORD dst_unused:UNUSED_PAD src0_sel:DWORD src1_sel:BYTE_0
	v_and_b32_e32 v9, 32, v9
	v_bfe_i32 v4, v4, 0, 16
	v_add_lshl_u32 v5, v9, v4, 1
	s_waitcnt vmcnt(5)
	v_lshl_add_u32 v154, v7, 11, v5
	s_waitcnt vmcnt(4)
	v_lshl_add_u32 v156, v6, 11, v5
	v_bfe_i32 v5, v8, 27, 1
	v_lshrrev_b32_e32 v5, 22, v5
	v_add_u32_e32 v5, v0, v5
	v_and_b32_e32 v5, 0xfffffc00, v5
	v_sub_u32_e32 v0, v0, v5
	v_lshrrev_b32_e32 v5, 4, v0
	v_ashrrev_i32_e32 v6, 31, v8
	v_bitop3_b32 v0, v5, v0, 32 bitop3:0x6c
	v_lshrrev_b32_e32 v6, 26, v6
	v_ashrrev_i32_e32 v5, 31, v0
	v_add_u32_e32 v6, v8, v6
	v_lshrrev_b32_e32 v5, 26, v5
	v_ashrrev_i32_e32 v6, 6, v6
	v_add_u32_e32 v7, v0, v5
	v_lshlrev_b32_e32 v9, 3, v6
	v_ashrrev_i32_e32 v5, 6, v7
	v_and_b32_e32 v9, -16, v9
	v_add_u32_e32 v9, v5, v9
	v_and_b32_e32 v10, 3, v5
	v_lshrrev_b32_e32 v11, 2, v9
	v_lshlrev_b32_e32 v12, 1, v9
	v_and_b32_e32 v7, 0xc0, v7
	s_ashr_i32 s9, s6, 6
	v_and_or_b32 v10, v9, s4, v10
	v_and_b32_e32 v11, 4, v11
	v_and_b32_e32 v12, 24, v12
	v_sub_u32_e32 v0, v0, v7
	s_ashr_i32 s8, s6, 8
	s_lshl_b32 s33, s9, 10
	v_or3_b32 v10, v10, v11, v12
	v_lshlrev_b32_e32 v11, 5, v6
	v_ashrrev_i16_sdwa v0, v213, sext(v0) dst_sel:DWORD dst_unused:UNUSED_PAD src0_sel:DWORD src1_sel:BYTE_0
	v_readlane_b32 s4, v254, 46
	v_and_b32_e32 v11, 32, v11
	v_bfe_i32 v7, v0, 0, 16
	v_readlane_b32 s5, v254, 47
	s_add_u32 s46, s2, s4
	v_add_lshl_u32 v11, v11, v7, 1
	s_addc_u32 s47, s3, s5
	s_add_i32 s50, s33, 0
	v_lshl_add_u32 v0, v10, 11, v11
	s_add_i32 m0, s50, 0x10000
	v_lshl_add_u32 v158, v9, 11, v11
	global_load_lds_dwordx4 v0, s[46:47]
	s_add_i32 m0, s50, 0x12000
	s_add_u32 s4, s46, 0x40000
	global_load_lds_dwordx4 v154, s[46:47]
	s_addc_u32 s5, s47, 0
	s_add_i32 m0, s50, 0x14000
	s_add_i32 s51, s50, 0x2000
	global_load_lds_dwordx4 v0, s[4:5]
	s_add_i32 m0, s50, 0x16000
	s_add_i32 s52, s50, 0x4000
	global_load_lds_dwordx4 v154, s[4:5]
	v_readlane_b32 s4, v254, 48
	s_mov_b32 m0, s50
	v_readlane_b32 s5, v254, 49
	s_add_i32 s53, s50, 0x6000
	s_cmp_eq_u32 s8, 1
	s_nop 2
	global_load_lds_dwordx4 v158, s[4:5]
	s_mov_b32 m0, s51
	s_nop 0
	global_load_lds_dwordx4 v156, s[4:5]
	v_readlane_b32 s4, v254, 50
	s_mov_b32 m0, s52
	v_readlane_b32 s5, v254, 51
	s_nop 4
	global_load_lds_dwordx4 v158, s[4:5]
	s_mov_b32 m0, s53
	s_nop 0
	global_load_lds_dwordx4 v156, s[4:5]
	s_cselect_b64 s[4:5], -1, 0
	s_cmp_lg_u32 s8, 1
	s_cbranch_scc1 .LBB0_666
	s_setprio 1
	s_barrier

; #define PG8_WAIT_V(n) asm volatile("s_waitcnt vmcnt(" #n ")" ::: "memory")
; #define PG8_BAR __builtin_amdgcn_s_barrier()
; template <class Epi, class Sched, bool ALIGN_EPI = false, bool SP2 = false>
; __device__ __forceinline__ void gemm_phase(PG8_LAS unsigned char* lds, const Gemm g, const Sched& S, const Epi& E) {
;     ...
;     PG8_WAIT_V(0);
;     if constexpr (!ALIGN_EPI) { if (wr == 0) PG8_BAR; }
;     PG8_BAR;
.LBB0_702:
	s_setprio 0
	s_waitcnt vmcnt(0)
	s_movk_i32 s27, 0x2000
	s_mov_b32 s33, 0x40000
	s_mov_b32 s42, 0x42000
	s_barrier

; #define PG8_STAGE(bufoff, gbase, voff) do { _Pragma("unroll") for (int _i = 0; _i < 2; ++_i) \
;         __builtin_amdgcn_global_load_lds((const unsigned*)((const char*)(gbase) + (voff)[_i]), (PG8_LAS unsigned*)(lds + (bufoff) + ldsw + _i * 8192), 16, 0, 0); } while (0)
; #define PG8_BAR __builtin_amdgcn_s_barrier()
;     __device__ __forceinline__ PrepRegs prep_issue(const Unit& u, int tid) const { return rs_issue(SSQ, u, tid); }
;     __device__ __forceinline__ PrepRegs prep_issue(const Unit& u, int tid) const { return rs_issue(SSQ, u, tid); }
; template <class Epi, class Sched, bool ALIGN_EPI = false, bool SP2 = false>
; __device__ __forceinline__ void gemm_phase(PG8_LAS unsigned char* lds, const Gemm g, const Sched& S, const Epi& E) {
;     ...
;     const int tid = tid_o, wid = __builtin_amdgcn_readfirstlane(tid >> 6), lane = tid & 63, wr = wid >> 2, wc = wid & 3, fr = lane & 15, fq = lane >> 4;
;     const int K = g.K, nt = K / BK;
;     unsigned voffA[2], voffB[2];
; #pragma unroll
;     for (int i = 0; i < 2; ++i) { int R, C; stage_rc(tid * 16 + i * 8192, R, C); const int Rb = Epi::PERM ? ((R & ~31) + perm32(R & 31)) : R;
;         voffA[i] = (unsigned)(R * K + C) * 2u; voffB[i] = (unsigned)(Rb * K + C) * 2u; }
;     const size_t kstep = (size_t)(BK * 2);
;     const size_t hstep = (size_t)HALF * K * 2;
;     const size_t tstep = 2 * hstep;
;     const unsigned ldsw = (unsigned)wid * 1024u;
;     const int aoff = lds_byte(wr * 64 + fr, fq * 8), boff = lds_byte(wc * 32 + fr, fq * 8);
;     ...
;     Unit cur, nxt; int ui = 0;
;     if (!S.next(0, cur)) return;
;     f32x4 acc[2][2][4][2];
; #pragma unroll
;     for (int a = 0; a < 2; ++a)
; #pragma unroll
;         for (int b = 0; b < 2; ++b)
; #pragma unroll
;             for (int m = 0; m < 4; ++m)
; #pragma unroll
;                 for (int n = 0; n < 2; ++n) acc[a][b][m][n] = (f32x4){0.f, 0.f, 0.f, 0.f};
;     bf16x8 At[4][2], B0[2][2], B1[2][2];
;     const char* cA = (const char*)g.A + (size_t)cur.pm * tstep; const char* cB = (const char*)g.Bt + (size_t)cur.pn * tstep;
;     S.a_ready(cur);
;     { const auto pr0 = E.prep_issue(cur, tid); E.prep_commit(lds, pr0, 0, tid); }
;     if constexpr (SP2) {
;         PG8_STAGE(PG8_SB(0, 0), cB, voffB); PG8_STAGE(PG8_SB(0, 1), cB + hstep, voffB); PG8_STAGE(PG8_SA(0, 0), cA, voffA); PG8_STAGE(PG8_SA(0, 1), cA + hstep, voffA);
;         if (wr == 1) PG8_BAR;
.LBB0_773:
	s_or_b64 exec, exec, s[4:5]
	s_waitcnt lgkmcnt(0)
	v_ashrrev_i32_e32 v3, 31, v6
	v_lshrrev_b32_e32 v3, 26, v3
	v_add_u32_e32 v3, v6, v3
	v_ashrrev_i32_e32 v7, 6, v3
	v_bfe_i32 v3, v6, 27, 1
	v_lshlrev_b32_e32 v2, 4, v6
	v_lshrrev_b32_e32 v3, 22, v3
	v_add_u32_e32 v3, v2, v3
	v_and_b32_e32 v3, 0xfffffc00, v3
	v_sub_u32_e32 v3, v2, v3
	v_lshrrev_b32_e32 v4, 4, v3
	v_bitop3_b32 v3, v4, v3, 32 bitop3:0x6c
	v_ashrrev_i32_e32 v5, 31, v3
	v_lshrrev_b32_e32 v5, 26, v5
	v_add_u32_e32 v5, v3, v5
	v_lshlrev_b32_e32 v4, 3, v7
	v_ashrrev_i32_e32 v8, 6, v5
	v_and_b32_e32 v5, 0xc0, v5
	v_and_b32_e32 v4, -16, v4
	v_sub_u32_e32 v3, v3, v5
	v_readlane_b32 s4, v254, 28
	v_add_u32_e32 v4, v8, v4
	v_lshlrev_b32_e32 v9, 5, v7
	v_ashrrev_i16_sdwa v3, v213, sext(v3) dst_sel:DWORD dst_unused:UNUSED_PAD src0_sel:DWORD src1_sel:BYTE_0
	s_add_u32 s48, s2, s4
	v_and_b32_e32 v10, 32, v9
	v_bfe_i32 v9, v3, 0, 16
	v_lshlrev_b32_e32 v3, 1, v4
	v_lshrrev_b32_e32 v5, 2, v4
	v_and_b32_e32 v11, 3, v8
	s_mov_b32 s4, 0x1fffe0
	v_and_b32_e32 v3, 24, v3
	v_and_b32_e32 v5, 4, v5
	v_and_or_b32 v11, v4, s4, v11
	v_or3_b32 v3, v11, v5, v3
	v_add_lshl_u32 v5, v10, v9, 1
	v_add_u32_e32 v2, 0x2000, v2
	v_lshl_add_u32 v140, v3, 11, v5
	v_ashrrev_i32_e32 v3, 31, v2
	v_lshrrev_b32_e32 v3, 22, v3
	v_add_u32_e32 v3, v2, v3
	v_ashrrev_i32_e32 v10, 10, v3
	v_mul_i32_i24_e32 v3, 0x400, v10
	v_sub_u32_e32 v2, v2, v3
	v_lshrrev_b32_e32 v3, 4, v2
	v_bitop3_b32 v2, v3, v2, 32 bitop3:0x6c
	v_lshl_add_u32 v138, v4, 11, v5
	v_ashrrev_i32_e32 v4, 31, v2
	v_lshrrev_b32_e32 v4, 26, v4
	v_add_u32_e32 v4, v2, v4
	v_readlane_b32 s5, v254, 29
	v_lshlrev_b32_e32 v3, 3, v10
	v_ashrrev_i32_e32 v11, 6, v4
	v_and_b32_e32 v4, 0xc0, v4
	s_addc_u32 s49, s3, s5
	v_and_b32_e32 v3, -16, v3
	v_sub_u32_e32 v2, v2, v4
	s_ashr_i32 s9, s6, 6
	v_add_u32_e32 v3, v11, v3
	v_ashrrev_i16_sdwa v2, v213, sext(v2) dst_sel:DWORD dst_unused:UNUSED_PAD src0_sel:DWORD src1_sel:BYTE_0
	s_lshl_b32 s33, s9, 10
	v_lshlrev_b32_e32 v5, 5, v10
	v_bfe_i32 v12, v2, 0, 16
	v_lshlrev_b32_e32 v2, 1, v3
	v_lshrrev_b32_e32 v4, 2, v3
	v_and_b32_e32 v13, 3, v11
	s_add_i32 s52, s33, 0
	v_and_b32_e32 v5, 32, v5
	v_and_b32_e32 v2, 24, v2
	v_and_b32_e32 v4, 4, v4
	v_and_or_b32 v13, v3, s4, v13
	s_add_i32 m0, s52, 0x10000
	s_ashr_i32 s8, s6, 8
	v_or3_b32 v2, v13, v4, v2
	v_add_lshl_u32 v4, v5, v12, 1
	global_load_lds_dwordx4 v140, s[48:49]
	s_add_i32 m0, s52, 0x12000
	v_lshl_add_u32 v144, v2, 11, v4
	s_add_u32 s4, s48, 0x40000
	global_load_lds_dwordx4 v144, s[48:49]
	s_addc_u32 s5, s49, 0
	s_add_i32 m0, s52, 0x14000
	s_add_i32 s53, s52, 0x2000
	global_load_lds_dwordx4 v140, s[4:5]
	s_add_i32 m0, s52, 0x16000
	v_lshl_add_u32 v142, v3, 11, v4
	global_load_lds_dwordx4 v144, s[4:5]
	v_readlane_b32 s4, v254, 33
	s_mov_b32 m0, s52
	v_readlane_b32 s5, v254, 34
	s_add_i32 s54, s52, 0x4000
	s_add_i32 s55, s52, 0x6000
	v_mov_b32_e32 v141, v1
	v_mov_b32_e32 v145, v1
	s_cmp_eq_u32 s8, 1
	global_load_lds_dwordx4 v138, s[4:5]
	s_mov_b32 m0, s53
	v_lshl_add_u64 v[2:3], s[48:49], 0, v[140:141]
	global_load_lds_dwordx4 v142, s[4:5]
	v_readlane_b32 s4, v254, 35
	s_mov_b32 m0, s54
	v_readlane_b32 s5, v254, 36
	v_lshl_add_u64 v[4:5], s[48:49], 0, v[144:145]
	s_nop 3
	global_load_lds_dwordx4 v138, s[4:5]
	s_mov_b32 m0, s55
	s_nop 0
	global_load_lds_dwordx4 v142, s[4:5]
	s_cselect_b64 s[4:5], -1, 0
	s_cmp_lg_u32 s8, 1
	s_cbranch_scc1 .LBB0_775
	s_setprio 1
	s_barrier

; #define PG8_STAGE(bufoff, gbase, voff) do { _Pragma("unroll") for (int _i = 0; _i < 2; ++_i) \
;         __builtin_amdgcn_global_load_lds((const unsigned*)((const char*)(gbase) + (voff)[_i]), (PG8_LAS unsigned*)(lds + (bufoff) + ldsw + _i * 8192), 16, 0, 0); } while (0)
; #define PG8_BAR __builtin_amdgcn_s_barrier()
;     __device__ __forceinline__ PrepRegs prep_issue(const Unit& u, int tid) const { return rs_issue(SSQ, u, tid); }
;     __device__ __forceinline__ PrepRegs prep_issue(const Unit& u, int tid) const { return rs_issue(SSQ, u, tid); }
; template <class Epi, class Sched, bool ALIGN_EPI = false, bool SP2 = false>
; __device__ __forceinline__ void gemm_phase(PG8_LAS unsigned char* lds, const Gemm g, const Sched& S, const Epi& E) {
;     ...
;     const int tid = tid_o, wid = __builtin_amdgcn_readfirstlane(tid >> 6), lane = tid & 63, wr = wid >> 2, wc = wid & 3, fr = lane & 15, fq = lane >> 4;
;     const int K = g.K, nt = K / BK;
;     unsigned voffA[2], voffB[2];
; #pragma unroll
;     for (int i = 0; i < 2; ++i) { int R, C; stage_rc(tid * 16 + i * 8192, R, C); const int Rb = Epi::PERM ? ((R & ~31) + perm32(R & 31)) : R;
;         voffA[i] = (unsigned)(R * K + C) * 2u; voffB[i] = (unsigned)(Rb * K + C) * 2u; }
;     const size_t kstep = (size_t)(BK * 2);
;     const size_t hstep = (size_t)HALF * K * 2;
;     const size_t tstep = 2 * hstep;
;     const unsigned ldsw = (unsigned)wid * 1024u;
;     const int aoff = lds_byte(wr * 64 + fr, fq * 8), boff = lds_byte(wc * 32 + fr, fq * 8);
;     ...
;     Unit cur, nxt; int ui = 0;
;     if (!S.next(0, cur)) return;
;     f32x4 acc[2][2][4][2];
; #pragma unroll
;     for (int a = 0; a < 2; ++a)
; #pragma unroll
;         for (int b = 0; b < 2; ++b)
; #pragma unroll
;             for (int m = 0; m < 4; ++m)
; #pragma unroll
;                 for (int n = 0; n < 2; ++n) acc[a][b][m][n] = (f32x4){0.f, 0.f, 0.f, 0.f};
;     bf16x8 At[4][2], B0[2][2], B1[2][2];
;     const char* cA = (const char*)g.A + (size_t)cur.pm * tstep; const char* cB = (const char*)g.Bt + (size_t)cur.pn * tstep;
;     S.a_ready(cur);
;     { const auto pr0 = E.prep_issue(cur, tid); E.prep_commit(lds, pr0, 0, tid); }
;     if constexpr (SP2) {
;         PG8_STAGE(PG8_SB(0, 0), cB, voffB); PG8_STAGE(PG8_SB(0, 1), cB + hstep, voffB); PG8_STAGE(PG8_SA(0, 0), cA, voffA); PG8_STAGE(PG8_SA(0, 1), cA + hstep, voffA);
;         if (wr == 1) PG8_BAR;
.LBB0_851:
	s_mov_b32 s79, 0x42000
	s_mov_b32 s78, 0x40000
	s_movk_i32 s76, 0x2000
	s_or_b64 exec, exec, s[4:5]
	v_readlane_b32 s2, v255, 4
	s_add_u32 s2, s2, 0x1200000
	v_readlane_b32 s3, v255, 5
	v_mov_b32_e32 v10, v212
	s_waitcnt lgkmcnt(0)
	s_barrier
	s_addc_u32 s3, s3, 0
	s_and_b64 vcc, exec, s[38:39]
	v_readfirstlane_b32 s6, v10
	s_cbranch_vccnz .LBB0_1006
	v_lshlrev_b32_e32 v0, 4, v10
	v_add_u32_e32 v3, 0x2000, v0
	v_ashrrev_i32_e32 v2, 31, v3
	v_lshrrev_b32_e32 v2, 22, v2
	v_add_u32_e32 v2, v3, v2
	v_ashrrev_i32_e32 v2, 10, v2
	v_mul_i32_i24_e32 v4, 0x400, v2
	v_sub_u32_e32 v3, v3, v4
	v_lshrrev_b32_e32 v4, 4, v3
	v_bitop3_b32 v5, v4, v3, 32 bitop3:0x6c
	v_ashrrev_i32_e32 v3, 31, v5
	v_lshrrev_b32_e32 v3, 26, v3
	v_add_u32_e32 v6, v5, v3
	v_lshlrev_b32_e32 v4, 3, v2
	v_ashrrev_i32_e32 v3, 6, v6
	v_and_b32_e32 v4, -16, v4
	v_add_u32_e32 v7, v3, v4
	v_and_b32_e32 v4, 3, v3
	s_mov_b32 s5, 0xffffe0
	v_lshrrev_b32_e32 v8, 2, v7
	v_lshlrev_b32_e32 v9, 1, v7
	v_and_or_b32 v4, v7, s5, v4
	v_and_b32_e32 v8, 4, v8
	v_and_b32_e32 v9, 24, v9
	v_and_b32_e32 v6, 0xc0, v6
	v_or3_b32 v4, v4, v8, v9
	v_sub_u32_e32 v5, v5, v6
	v_mul_u32_u24_e32 v8, 0xb00, v4
	v_lshlrev_b32_e32 v4, 5, v2
	v_ashrrev_i16_sdwa v5, v213, sext(v5) dst_sel:DWORD dst_unused:UNUSED_PAD src0_sel:DWORD src1_sel:BYTE_0
	v_and_b32_e32 v4, 32, v4
	v_bfe_i32 v5, v5, 0, 16
	s_movk_i32 s4, 0xb00
	v_add_u32_e32 v6, v4, v5
	v_mul_lo_u32 v7, v7, s4
	v_add_lshl_u32 v158, v8, v6, 1
	v_add_lshl_u32 v160, v6, v7, 1
	v_bfe_i32 v6, v10, 27, 1
	v_lshrrev_b32_e32 v6, 22, v6
	v_add_u32_e32 v6, v0, v6
	v_and_b32_e32 v6, 0xfffffc00, v6
	v_sub_u32_e32 v0, v0, v6
	v_lshrrev_b32_e32 v6, 4, v0
	v_ashrrev_i32_e32 v7, 31, v10
	v_bitop3_b32 v0, v6, v0, 32 bitop3:0x6c
	v_lshrrev_b32_e32 v7, 26, v7
	v_ashrrev_i32_e32 v6, 31, v0
	v_add_u32_e32 v7, v10, v7
	v_lshrrev_b32_e32 v6, 26, v6
	v_ashrrev_i32_e32 v7, 6, v7
	v_add_u32_e32 v9, v0, v6
	v_lshlrev_b32_e32 v8, 3, v7
	v_ashrrev_i32_e32 v6, 6, v9
	v_and_b32_e32 v8, -16, v8
	v_add_u32_e32 v11, v6, v8
	v_and_b32_e32 v8, 3, v6
	v_lshrrev_b32_e32 v12, 2, v11
	v_lshlrev_b32_e32 v13, 1, v11
	v_and_or_b32 v8, v11, s5, v8
	v_and_b32_e32 v12, 4, v12
	v_and_b32_e32 v13, 24, v13
	v_and_b32_e32 v9, 0xc0, v9
	s_ashr_i32 s9, s6, 6
	v_or3_b32 v8, v8, v12, v13
	v_sub_u32_e32 v0, v0, v9
	v_readlane_b32 s5, v254, 26
	s_ashr_i32 s8, s6, 8
	s_lshl_b32 s33, s9, 10
	v_mul_u32_u24_e32 v12, 0xb00, v8
	v_lshlrev_b32_e32 v8, 5, v7
	v_ashrrev_i16_sdwa v0, v213, sext(v0) dst_sel:DWORD dst_unused:UNUSED_PAD src0_sel:DWORD src1_sel:BYTE_0
	v_mul_lo_u32 v11, v11, s4
	s_mul_i32 s4, s5, 0x160000
	v_and_b32_e32 v8, 32, v8
	v_bfe_i32 v9, v0, 0, 16
	s_add_u32 s44, s2, s4
	s_mul_hi_i32 s4, s5, 0x160000
	v_add_u32_e32 v13, v8, v9
	s_addc_u32 s45, s3, s4
	s_add_i32 s48, s33, 0
	v_add_lshl_u32 v0, v12, v13, 1
	s_add_i32 m0, s48, 0x10000
	v_add_lshl_u32 v162, v13, v11, 1
	global_load_lds_dwordx4 v0, s[44:45]
	s_add_i32 m0, s48, 0x12000
	s_add_u32 s4, s44, 0xb0000
	global_load_lds_dwordx4 v158, s[44:45]
	s_addc_u32 s5, s45, 0
	s_add_i32 m0, s48, 0x14000
	s_add_i32 s49, s48, 0x2000
	global_load_lds_dwordx4 v0, s[4:5]
	s_add_i32 m0, s48, 0x16000
	s_add_i32 s50, s48, 0x4000
	global_load_lds_dwordx4 v158, s[4:5]
	v_readlane_b32 s4, v254, 54
	s_mov_b32 m0, s48
	v_readlane_b32 s5, v254, 55
	s_add_i32 s51, s48, 0x6000
	s_cmp_eq_u32 s8, 1
	s_mov_b32 s77, 0x7fc01ff1
	s_nop 1
	global_load_lds_dwordx4 v162, s[4:5]
	s_mov_b32 m0, s49
	s_nop 0
	global_load_lds_dwordx4 v160, s[4:5]
	v_readlane_b32 s4, v254, 56
	s_mov_b32 m0, s50
	v_readlane_b32 s5, v254, 57
	s_nop 4
	global_load_lds_dwordx4 v162, s[4:5]
	s_mov_b32 m0, s51
	s_nop 0
	global_load_lds_dwordx4 v160, s[4:5]
	s_cselect_b64 s[4:5], -1, 0
	s_cmp_lg_u32 s8, 1
	s_cbranch_scc1 .LBB0_854
	s_setprio 1
	s_barrier
